# rnn pass 1: max(1-a*a,0) folded into the fma as a VOP3 clamp (16 VALU ops fewer per unit-thread), results bit-identical
# speedup vs baseline: 1.0014x; 1.0014x over previous
; #define LAS __attribute__((address_space(3)))
; DI float sigm(float x) { return __builtin_amdgcn_rcpf(1.0f + __builtin_amdgcn_exp2f(-x * LOG2E)); }
; #define MFMA32(a, b, c) __builtin_amdgcn_mfma_f32_32x32x16_bf16((a), (b), (c), 0, 0, 0)
; DI void rnn_phase(LAS unsigned char* lds, bf16_t* P, const bf16_t* WaT, const bf16_t* WiT, const float* convw, const float* convb, const float* ba, const float* bi, const float* lam,
;                   f32x2* sums, unsigned* au, bool fin, int bx, int G, int tid, int wid, int lane) {
;     ...
;             f32x16 aR, aI;
; #pragma unroll
;             for (int i = 0; i < 16; ++i) { aR[i] = 0.f; aI[i] = 0.f; }
; #pragma unroll
;             for (int s = 0; s < 4; ++s) {
;                 const bf16x8 af = *(const LAS bf16x8*)(XB + (32 * tt + l32) * 72 + 16 * s + 8 * hl);
;                 const bf16x8 bR = *(const LAS bf16x8*)(WL + (32 * nt + l32) * 72 + 16 * s + 8 * hl);
;                 const bf16x8 bI = *(const LAS bf16x8*)(WL + 64 * 72 + (32 * nt + l32) * 72 + 16 * s + 8 * hl);
;                 aR = MFMA32(af, bR, aR); aI = MFMA32(af, bI, aI);
;             }
;             const int ch = 32 * nt + l32;
;             float At = 1.f, Ht = 0.f;
; #pragma unroll
;             for (int g = 0; g < 4; ++g) {
;                 float A = 1.f, H = 0.f;
; #pragma unroll
;                 for (int q4 = 0; q4 < 4; ++q4) { const int i = 4 * g + q4, tok = 32 * tt + 8 * g + 4 * hl + q4;
;                     const float r = sigm(aR[i] + bac), ig = sigm(aI[i] + bic);
;                     const float a = __builtin_amdgcn_exp2f(k8c * r);
;                     const float uu_ = __builtin_amdgcn_sqrtf(fmaxf(1.0f - a * a, 0.f)) * ig * XC[tok * 64 + ch];
;                     { const h2_t pv = {(_Float16)(1.0f - a), (_Float16)uu_}; au[(rowbase + tok) * D + ch0 + ch] = __builtin_bit_cast(unsigned, pv); }
;                     H = a * H + uu_; A *= a; }
.LBB0_360:
	v_mov_b32_e32 v210, 0xbfb8aa3b
	v_mul_f32_e32 v211, v210, v75
	v_mul_f32_e32 v212, v210, v143
	s_waitcnt lgkmcnt(0)
	s_barrier
	ds_read_b128 v[0:3], v120
	ds_read_b128 v[4:7], v121
	s_ashr_i32 s58, s18, 10
	s_waitcnt lgkmcnt(0)
	v_mfma_f32_32x32x16_bf16 v[16:31], v[0:3], v[4:7], 0
	ds_read_b128 v[4:7], v122
	ds_read_b128 v[150:153], v120 offset:32
	ds_read_b128 v[154:157], v121 offset:32
	s_bfe_u32 s21, s18, 0x60004
	s_ashr_i32 s59, s58, 31
	s_lshl_b64 s[60:61], s[58:59], 13
	s_lshl_b32 s12, s21, 7
	s_or_b32 s60, s60, s12
	s_waitcnt lgkmcnt(0)
	v_mfma_f32_32x32x16_bf16 v[0:15], v[0:3], v[4:7], 0
	s_lshl_b32 s88, s63, 2
	v_lshl_add_u64 v[82:83], v[78:79], 0, s[88:89]
	v_mov_b64_e32 v[208:209], s[60:61]
	v_lshlrev_b64 v[208:209], 12, v[208:209]
	v_lshl_add_u64 v[208:209], v[82:83], 0, v[208:209]
	v_mfma_f32_32x32x16_bf16 v[16:31], v[150:153], v[154:157], v[16:31]
	ds_read_b128 v[154:157], v122 offset:32
	s_waitcnt lgkmcnt(0)
	v_mfma_f32_32x32x16_bf16 v[0:15], v[150:153], v[154:157], v[0:15]
	ds_read_b128 v[150:153], v120 offset:64
	ds_read_b128 v[154:157], v121 offset:64
	s_waitcnt lgkmcnt(0)
	v_mfma_f32_32x32x16_bf16 v[16:31], v[150:153], v[154:157], v[16:31]
	ds_read_b128 v[154:157], v120 offset:96
	ds_read_b128 v[158:161], v121 offset:96
	ds_read_b128 v[172:175], v122 offset:96
	s_waitcnt lgkmcnt(0)
	v_mfma_f32_32x32x16_bf16 v[16:31], v[154:157], v[158:161], v[16:31]
	ds_read_b128 v[158:161], v122 offset:64
	s_waitcnt lgkmcnt(0)
	v_mfma_f32_32x32x16_bf16 v[0:15], v[150:153], v[158:161], v[0:15]
	s_nop 8
	v_fma_f32 v16, v16, v210, v211
	v_exp_f32_e32 v16, v16
	v_fma_f32 v17, v17, v210, v211
	v_exp_f32_e32 v80, v17
	v_add_f32_e32 v16, 1.0, v16
	v_mfma_f32_32x32x16_bf16 v[0:15], v[154:157], v[172:175], v[0:15]
	v_rcp_f32_e32 v16, v16
	v_add_f32_e32 v80, 1.0, v80
	v_rcp_f32_e32 v80, v80
	ds_read_b32 v147, v127
	ds_read_b32 v149, v128
	ds_read_b32 v150, v129
	ds_read_b32 v151, v130
	ds_read_b32 v152, v131
	ds_read_b32 v153, v132
	ds_read_b32 v154, v133
	ds_read_b32 v155, v134
	v_mul_f32_e32 v16, v144, v16
	v_exp_f32_e32 v69, v16
	v_fma_f32 v0, v0, v210, v212
	v_exp_f32_e32 v0, v0
	v_fma_f32 v16, -v69, v69, 1.0 clamp
	v_sqrt_f32_e32 v145, v16
	v_add_f32_e32 v0, 1.0, v0
	v_rcp_f32_e32 v0, v0
	v_fma_f32 v1, v1, v210, v212
	v_mul_f32_e32 v0, v0, v145
	s_waitcnt lgkmcnt(0)
	v_mul_f32_e32 v145, v147, v0
	v_mul_f32_e32 v0, v144, v80
	v_exp_f32_e32 v80, v0
	v_exp_f32_e32 v147, v1
	v_sub_f32_e32 v146, 1.0, v69
	v_fma_f32 v17, -v80, v80, 1.0 clamp
	v_add_f32_e32 v16, 1.0, v147
	v_rcp_f32_e32 v16, v16
	v_sqrt_f32_e32 v17, v17
	v_cvt_pk_f16_f32 v146, v146, v145
	v_lshl_add_u64 v[0:1], v[176:177], 0, v[208:209]
	global_store_dword v[0:1], v146, off
	v_fma_f32 v1, v18, v210, v211
	v_mul_f32_e32 v0, v16, v17
	v_exp_f32_e32 v17, v1
	v_fma_f32 v2, v2, v210, v212
	v_exp_f32_e32 v2, v2
	v_add_f32_e32 v17, 1.0, v17
	v_rcp_f32_e32 v17, v17
	v_mul_f32_e32 v16, v149, v0
	v_sub_f32_e32 v0, 1.0, v80
	v_cvt_pk_f16_f32 v18, v0, v16
	v_mul_f32_e32 v17, v144, v17
	v_exp_f32_e32 v17, v17
	v_add_f32_e32 v2, 1.0, v2
	v_fma_f32 v146, -v17, v17, 1.0 clamp
	v_rcp_f32_e32 v2, v2
	v_sqrt_f32_e32 v146, v146
	v_lshl_add_u64 v[0:1], v[178:179], 0, v[208:209]
	global_store_dword v[0:1], v18, off
	v_fma_f32 v1, v19, v210, v211
	v_mul_f32_e32 v0, v2, v146
	v_exp_f32_e32 v2, v1
	v_fma_f32 v3, v3, v210, v212
	v_fmac_f32_e32 v145, 0, v69
	v_add_f32_e32 v2, 1.0, v2
	v_rcp_f32_e32 v2, v2
	v_fmac_f32_e32 v16, v80, v145
	v_mul_f32_e32 v18, v69, v80
	v_exp_f32_e32 v3, v3
	v_mul_f32_e32 v2, v144, v2
	v_exp_f32_e32 v80, v2
	v_mul_f32_e32 v69, v150, v0
	v_add_f32_e32 v2, 1.0, v3
	v_sub_f32_e32 v0, 1.0, v17
	v_fma_f32 v3, -v80, v80, 1.0 clamp
	v_cvt_pk_f16_f32 v19, v0, v69
	v_rcp_f32_e32 v2, v2
	v_sqrt_f32_e32 v3, v3
	v_lshl_add_u64 v[0:1], v[180:181], 0, v[208:209]
	global_store_dword v[0:1], v19, off
	v_fmac_f32_e32 v69, v17, v16
	v_mul_f32_e32 v1, v17, v18
	v_fma_f32 v17, v20, v210, v211
	v_mul_f32_e32 v0, v2, v3
	v_mul_f32_e32 v0, v151, v0
	v_sub_f32_e32 v2, 1.0, v80
	v_exp_f32_e32 v17, v17
	v_cvt_pk_f16_f32 v16, v2, v0
	v_lshl_add_u64 v[2:3], v[182:183], 0, v[208:209]
	global_store_dword v[2:3], v16, off
	v_add_f32_e32 v2, 1.0, v17
	v_rcp_f32_e32 v2, v2
	v_fma_f32 v3, v4, v210, v212
	v_exp_f32_e32 v3, v3
	v_mul_f32_e32 v2, v144, v2
	v_exp_f32_e32 v18, v2
	v_fma_f32 v5, v5, v210, v212
	v_add_f32_e32 v2, 1.0, v3
	v_rcp_f32_e32 v4, v2
	v_fma_f32 v2, -v18, v18, 1.0 clamp
	v_sqrt_f32_e32 v16, v2
	v_fmac_f32_e32 v0, v80, v69
	v_fma_f32 v6, v6, v210, v212
	v_mul_f32_e32 v4, v4, v16
	v_mul_f32_e32 v19, v152, v4
	v_fma_f32 v4, v21, v210, v211
	v_exp_f32_e32 v4, v4
	v_exp_f32_e32 v21, v5
	v_sub_f32_e32 v16, 1.0, v18
	v_cvt_pk_f16_f32 v20, v16, v19
	v_add_f32_e32 v4, 1.0, v4
	v_rcp_f32_e32 v4, v4
	v_exp_f32_e32 v6, v6
	v_mul_f32_e32 v4, v144, v4
	v_exp_f32_e32 v69, v4
	v_add_f32_e32 v16, 1.0, v21
	v_rcp_f32_e32 v16, v16
	v_fma_f32 v17, -v69, v69, 1.0 clamp
	v_sqrt_f32_e32 v17, v17
	v_lshl_add_u64 v[4:5], v[184:185], 0, v[208:209]
	global_store_dword v[4:5], v20, off
	v_fma_f32 v5, v22, v210, v211
	v_mul_f32_e32 v4, v16, v17
	v_exp_f32_e32 v17, v5
	v_mul_f32_e32 v16, v4, v153
	v_sub_f32_e32 v4, 1.0, v69
	v_cvt_pk_f16_f32 v20, v4, v16
	v_add_f32_e32 v17, 1.0, v17
	v_rcp_f32_e32 v17, v17
	v_add_f32_e32 v6, 1.0, v6
	v_mul_f32_e32 v17, v144, v17
	v_exp_f32_e32 v17, v17
	v_rcp_f32_e32 v6, v6
	v_lshl_add_u64 v[4:5], v[186:187], 0, v[208:209]
	global_store_dword v[4:5], v20, off
	v_fma_f32 v21, -v17, v17, 1.0 clamp
	v_sqrt_f32_e32 v21, v21
	v_fma_f32 v5, v23, v210, v211
	v_fma_f32 v7, v7, v210, v212
	v_mul_f32_e32 v4, v6, v21
	v_exp_f32_e32 v6, v5
	v_exp_f32_e32 v7, v7
	v_fmac_f32_e32 v19, 0, v18
	v_add_f32_e32 v6, 1.0, v6
	v_rcp_f32_e32 v6, v6
	v_fmac_f32_e32 v16, v69, v19
	v_mul_f32_e32 v19, v4, v154
	v_sub_f32_e32 v4, 1.0, v17
	v_mul_f32_e32 v6, v144, v6
	v_exp_f32_e32 v21, v6
	v_add_f32_e32 v6, 1.0, v7
	v_cvt_pk_f16_f32 v20, v4, v19
	v_fma_f32 v7, -v21, v21, 1.0 clamp
	v_rcp_f32_e32 v6, v6
	v_sqrt_f32_e32 v7, v7
	v_mul_f32_e32 v18, v18, v69
	v_lshl_add_u64 v[4:5], v[188:189], 0, v[208:209]
	global_store_dword v[4:5], v20, off
	v_fmac_f32_e32 v19, v17, v16
	v_mul_f32_e32 v5, v17, v18
	v_fma_f32 v17, v24, v210, v211
	v_mul_f32_e32 v4, v6, v7
	v_mul_f32_e32 v4, v4, v155
	v_sub_f32_e32 v6, 1.0, v21
	v_exp_f32_e32 v17, v17
	v_cvt_pk_f16_f32 v16, v6, v4
	v_lshl_add_u64 v[6:7], v[190:191], 0, v[208:209]
	global_store_dword v[6:7], v16, off
	v_add_f32_e32 v6, 1.0, v17
	v_rcp_f32_e32 v6, v6
	v_fma_f32 v7, v8, v210, v212
	v_exp_f32_e32 v7, v7
	v_mul_f32_e32 v6, v144, v6
	v_exp_f32_e32 v18, v6
	v_mul_f32_e32 v3, v80, v1
	v_add_f32_e32 v6, 1.0, v7
	v_rcp_f32_e32 v8, v6
	v_fma_f32 v6, -v18, v18, 1.0 clamp
	v_sqrt_f32_e32 v16, v6
	v_fmac_f32_e32 v4, v21, v19
	v_mul_f32_e32 v7, v21, v5
	v_fma_f32 v9, v9, v210, v212
	v_mul_f32_e32 v8, v8, v16
	ds_read_b32 v16, v135
	ds_read_b32 v19, v136
	ds_read_b32 v20, v137
	ds_read_b32 v21, v138
	ds_read_b32 v22, v139
	ds_read_b32 v23, v140
	ds_read_b32 v24, v141
	ds_read_b32 v69, v142
	s_waitcnt lgkmcnt(0)
; DI float sigm(float x) { return __builtin_amdgcn_rcpf(1.0f + __builtin_amdgcn_exp2f(-x * LOG2E)); }
; DI void rnn_phase(LAS unsigned char* lds, bf16_t* P, const bf16_t* WaT, const bf16_t* WiT, const float* convw, const float* convb, const float* ba, const float* bi, const float* lam,
;                   f32x2* sums, unsigned* au, bool fin, int bx, int G, int tid, int wid, int lane) {
;     ...
;                 for (int q4 = 0; q4 < 4; ++q4) { const int i = 4 * g + q4, tok = 32 * tt + 8 * g + 4 * hl + q4;
;                     const float r = sigm(aR[i] + bac), ig = sigm(aI[i] + bic);
;                     const float a = __builtin_amdgcn_exp2f(k8c * r);
;                     const float uu_ = __builtin_amdgcn_sqrtf(fmaxf(1.0f - a * a, 0.f)) * ig * XC[tok * 64 + ch];
;                     { const h2_t pv = {(_Float16)(1.0f - a), (_Float16)uu_}; au[(rowbase + tok) * D + ch0 + ch] = __builtin_bit_cast(unsigned, pv); }
;                     H = a * H + uu_; A *= a; }
;                 const float pA = __shfl_xor(A, 32), pH = __shfl_xor(H, 32);
;                 const float fA = hl ? pA : A, fH = hl ? pH : H, sA = hl ? A : pA, sH = hl ? H : pH;
;                 Ht = fA * Ht + fH; At *= fA; Ht = sA * Ht + sH; At *= sA;
;             }
;             if (hl == 0) { SG[tt * 64 + ch] = At; SG[256 + tt * 64 + ch] = Ht; }
	v_mul_f32_e32 v80, v8, v16
	v_fma_f32 v8, v25, v210, v211
	v_exp_f32_e32 v8, v8
	v_exp_f32_e32 v145, v9
	v_sub_f32_e32 v16, 1.0, v18
	v_add_f32_e32 v8, 1.0, v8
	v_rcp_f32_e32 v8, v8
	v_cvt_pk_f16_f32 v25, v16, v80
	v_fma_f32 v10, v10, v210, v212
	v_mul_f32_e32 v8, v144, v8
	v_exp_f32_e32 v146, v8
	v_add_f32_e32 v16, 1.0, v145
	v_rcp_f32_e32 v16, v16
	v_fma_f32 v17, -v146, v146, 1.0 clamp
	v_sqrt_f32_e32 v17, v17
	v_lshl_add_u64 v[8:9], v[192:193], 0, v[208:209]
	global_store_dword v[8:9], v25, off
	v_fma_f32 v9, v26, v210, v211
	v_mul_f32_e32 v8, v16, v17
	v_exp_f32_e32 v17, v9
	v_exp_f32_e32 v10, v10
	v_mul_f32_e32 v16, v8, v19
	v_add_f32_e32 v17, 1.0, v17
	v_rcp_f32_e32 v17, v17
	v_sub_f32_e32 v8, 1.0, v146
	v_cvt_pk_f16_f32 v19, v8, v16
	v_mul_f32_e32 v17, v144, v17
	v_exp_f32_e32 v17, v17
	v_add_f32_e32 v10, 1.0, v10
	v_rcp_f32_e32 v10, v10
	v_fma_f32 v25, -v17, v17, 1.0 clamp
	v_sqrt_f32_e32 v25, v25
	v_lshl_add_u64 v[8:9], v[194:195], 0, v[208:209]
	global_store_dword v[8:9], v19, off
	v_fma_f32 v9, v27, v210, v211
	v_mul_f32_e32 v8, v10, v25
	v_exp_f32_e32 v10, v9
	v_fma_f32 v11, v11, v210, v212
	v_exp_f32_e32 v11, v11
	v_add_f32_e32 v10, 1.0, v10
	v_rcp_f32_e32 v10, v10
	v_mul_f32_e32 v19, v8, v20
	v_sub_f32_e32 v8, 1.0, v17
	v_cvt_pk_f16_f32 v20, v8, v19
	v_mul_f32_e32 v10, v144, v10
	v_exp_f32_e32 v25, v10
	v_add_f32_e32 v10, 1.0, v11
	v_rcp_f32_e32 v10, v10
	v_fma_f32 v11, -v25, v25, 1.0 clamp
	v_sqrt_f32_e32 v11, v11
	v_fmac_f32_e32 v80, 0, v18
	v_fmac_f32_e32 v16, v146, v80
	v_mul_f32_e32 v18, v18, v146
	v_lshl_add_u64 v[8:9], v[196:197], 0, v[208:209]
	global_store_dword v[8:9], v20, off
	v_fmac_f32_e32 v19, v17, v16
	v_mul_f32_e32 v9, v17, v18
	v_fma_f32 v17, v28, v210, v211
	v_mul_f32_e32 v8, v10, v11
	v_mul_f32_e32 v8, v8, v21
	v_sub_f32_e32 v10, 1.0, v25
	v_exp_f32_e32 v17, v17
	v_cvt_pk_f16_f32 v16, v10, v8
	v_lshl_add_u64 v[10:11], v[198:199], 0, v[208:209]
	global_store_dword v[10:11], v16, off
	v_add_f32_e32 v10, 1.0, v17
	v_rcp_f32_e32 v10, v10
	v_fma_f32 v11, v12, v210, v212
	v_exp_f32_e32 v11, v11
	v_mul_f32_e32 v10, v144, v10
	v_exp_f32_e32 v18, v10
	v_fmac_f32_e32 v8, v25, v19
	v_add_f32_e32 v10, 1.0, v11
	v_rcp_f32_e32 v12, v10
	v_fma_f32 v10, -v18, v18, 1.0 clamp
	v_sqrt_f32_e32 v16, v10
	v_fma_f32 v13, v13, v210, v212
	v_exp_f32_e32 v21, v13
	v_mul_f32_e32 v12, v12, v16
	v_mul_f32_e32 v19, v12, v22
	v_fma_f32 v12, v29, v210, v211
	v_exp_f32_e32 v12, v12
	v_sub_f32_e32 v16, 1.0, v18
	v_cvt_pk_f16_f32 v20, v16, v19
	v_add_f32_e32 v12, 1.0, v12
	v_rcp_f32_e32 v12, v12
	v_fmac_f32_e32 v19, 0, v18
	v_fma_f32 v14, v14, v210, v212
	v_mul_f32_e32 v12, v144, v12
	v_exp_f32_e32 v22, v12
	v_add_f32_e32 v16, 1.0, v21
	v_rcp_f32_e32 v16, v16
	v_fma_f32 v17, -v22, v22, 1.0 clamp
	v_sqrt_f32_e32 v17, v17
	v_lshl_add_u64 v[12:13], v[200:201], 0, v[208:209]
	global_store_dword v[12:13], v20, off
	v_fma_f32 v13, v30, v210, v211
	v_mul_f32_e32 v12, v16, v17
	v_mul_f32_e32 v16, v12, v23
	v_sub_f32_e32 v12, 1.0, v22
	v_exp_f32_e32 v17, v13
	v_cvt_pk_f16_f32 v20, v12, v16
	v_lshl_add_u64 v[12:13], v[202:203], 0, v[208:209]
	v_add_f32_e32 v17, 1.0, v17
	global_store_dword v[12:13], v20, off
	v_fma_f32 v13, v31, v210, v211
	v_rcp_f32_e32 v17, v17
	v_fmac_f32_e32 v16, v22, v19
	v_exp_f32_e32 v19, v13
	v_mul_f32_e32 v17, v144, v17
	v_exp_f32_e32 v17, v17
	v_exp_f32_e32 v14, v14
	v_add_f32_e32 v19, 1.0, v19
	v_rcp_f32_e32 v19, v19
	v_fma_f32 v21, -v17, v17, 1.0 clamp
	v_add_f32_e32 v14, 1.0, v14
	v_fma_f32 v15, v15, v210, v212
	v_mul_f32_e32 v19, v144, v19
	v_rcp_f32_e32 v14, v14
	v_sqrt_f32_e32 v21, v21
	v_exp_f32_e32 v19, v19
	v_exp_f32_e32 v15, v15
	v_mul_f32_e32 v12, v14, v21
	v_mul_f32_e32 v14, v12, v24
	v_fma_f32 v21, -v19, v19, 1.0 clamp
	v_add_f32_e32 v15, 1.0, v15
	v_sub_f32_e32 v12, 1.0, v17
	v_rcp_f32_e32 v15, v15
	v_sqrt_f32_e32 v21, v21
	v_cvt_pk_f16_f32 v20, v12, v14
	v_lshl_add_u64 v[12:13], v[204:205], 0, v[208:209]
	v_mul_f32_e32 v18, v18, v22
	global_store_dword v[12:13], v20, off
	v_mul_f32_e32 v12, v15, v21
	v_fmac_f32_e32 v14, v17, v16
	v_mul_f32_e32 v13, v17, v18
	v_mul_f32_e32 v12, v12, v69
	v_sub_f32_e32 v15, 1.0, v19
	v_mul_f32_e32 v11, v25, v9
	v_cvt_pk_f16_f32 v18, v15, v12
	v_fmac_f32_e32 v12, v19, v14
	v_mul_f32_e32 v15, v19, v13
	ds_bpermute_b32 v2, v123, v3
	ds_bpermute_b32 v1, v123, v0
	ds_bpermute_b32 v6, v123, v7
	ds_bpermute_b32 v5, v123, v4
	ds_bpermute_b32 v10, v123, v11
	ds_bpermute_b32 v9, v123, v8
	ds_bpermute_b32 v13, v123, v15
	ds_bpermute_b32 v14, v123, v12
	v_lshl_add_u64 v[16:17], v[206:207], 0, v[208:209]
	global_store_dword v[16:17], v18, off
	s_and_saveexec_b64 s[38:39], s[40:41]
	s_cbranch_execz .LBB0_362
	v_fmac_f32_e32 v0, 0, v3
	s_waitcnt lgkmcnt(0)
	v_mul_f32_e32 v16, v3, v2
	v_fmac_f32_e32 v1, v0, v2
	v_mul_f32_e32 v16, v7, v16
	v_fmac_f32_e32 v4, v7, v1
	v_mul_f32_e32 v16, v16, v6
	v_fmac_f32_e32 v5, v4, v6
	v_mul_f32_e32 v16, v11, v16
	v_fmac_f32_e32 v8, v11, v5
	v_mul_f32_e32 v16, v16, v10
	v_fmac_f32_e32 v9, v8, v10
	v_mul_f32_e32 v16, v15, v16
	v_fmac_f32_e32 v12, v15, v9
	v_mul_f32_e32 v16, v16, v13
	v_fmac_f32_e32 v14, v12, v13
	ds_write2st64_b32 v124, v16, v14 offset1:4
